# item-C bias add: 8 serialized divergent LDS reads rewritten as straight-line batch + cndmask; NaN-canonicalise v_max removed in attention max trees; quad barriers kept
# speedup vs baseline: 1.0097x; 1.0097x over previous
; __device__ __forceinline__ float qmax(float x) { float a = x, b = x; swap16(a, b); a = fmaxf(a, b); b = a; swap32(a, b); return fmaxf(a, b); }
; __device__ __forceinline__ void softmax_pv(float& m, float& l, f32x4 (&o)[4], f32x4 s0, f32x4 s1, const bf16x8 (&vf)[4], float kL2e) {
;     float mx = fmaxf(fmaxf(fmaxf(s0[0], s0[1]), fmaxf(s0[2], s0[3])), fmaxf(fmaxf(s1[0], s1[1]), fmaxf(s1[2], s1[3])));
;     mx = qmax(mx);
;     const float mn = fmaxf(m, mx);
;     if (__builtin_amdgcn_ballot_w64(mn > m) != 0ull) {
;         const float alpha = __builtin_amdgcn_exp2f((m - mn) * kL2e);
;         l *= alpha;
; #pragma unroll
;         for (int dt = 0; dt < 4; ++dt) o[dt] = o[dt] * alpha;
;         m = mn;
.LBB0_368:
	v_max_f32_e32 v156, v2, v204
	v_max_f32_e32 v157, v214, v215
	v_max_f32_e32 v3, v3, v3
	v_max_f32_e32 v158, v216, v216
	v_max_f32_e32 v3, v158, v3
	v_max3_f32 v3, v210, v212, v3
	v_max3_f32 v3, v156, v157, v3
	v_mov_b32_e32 v156, v3
	s_nop 1
	v_permlane16_swap_b32 v3, v156
	s_nop 1
	s_nop 0
	v_max_f32_e32 v3, v3, v156
	v_mov_b32_e32 v156, v3
	s_nop 1
	v_permlane32_swap_b32 v3, v156
	s_nop 1
	s_nop 0
	v_max3_f32 v179, v0, v3, v156
	v_cmp_gt_f32_e32 vcc, v179, v0
	s_cbranch_vccz .LBB0_370
	v_sub_f32_e32 v0, v0, v179
	v_mul_f32_e32 v0, v174, v0
	v_exp_f32_e32 v0, v0
	s_nop 0
	v_mul_f32_e32 v192, v192, v0
	v_pk_mul_f32 v[94:95], v[94:95], v[0:1] op_sel_hi:[1,0]
	v_pk_mul_f32 v[92:93], v[92:93], v[0:1] op_sel_hi:[1,0]
	v_pk_mul_f32 v[98:99], v[98:99], v[0:1] op_sel_hi:[1,0]
	v_pk_mul_f32 v[96:97], v[96:97], v[0:1] op_sel_hi:[1,0]
	v_pk_mul_f32 v[90:91], v[90:91], v[0:1] op_sel_hi:[1,0]
	v_pk_mul_f32 v[88:89], v[88:89], v[0:1] op_sel_hi:[1,0]
	v_pk_mul_f32 v[86:87], v[86:87], v[0:1] op_sel_hi:[1,0]
	v_pk_mul_f32 v[84:85], v[84:85], v[0:1] op_sel_hi:[1,0]
	s_branch .LBB0_371

; __device__ __forceinline__ float qmax(float x) { float a = x, b = x; swap16(a, b); a = fmaxf(a, b); b = a; swap32(a, b); return fmaxf(a, b); }
; __device__ __forceinline__ void softmax_pv(float& m, float& l, f32x4 (&o)[4], f32x4 s0, f32x4 s1, const bf16x8 (&vf)[4], float kL2e) {
;     float mx = fmaxf(fmaxf(fmaxf(s0[0], s0[1]), fmaxf(s0[2], s0[3])), fmaxf(fmaxf(s1[0], s1[1]), fmaxf(s1[2], s1[3])));
;     mx = qmax(mx);
;     const float mn = fmaxf(m, mx);
;     if (__builtin_amdgcn_ballot_w64(mn > m) != 0ull) {
;         const float alpha = __builtin_amdgcn_exp2f((m - mn) * kL2e);
;         l *= alpha;
; #pragma unroll
;         for (int dt = 0; dt < 4; ++dt) o[dt] = o[dt] * alpha;
;         m = mn;
.LBB0_375:
	v_max_f32_e32 v2, v217, v217
	s_nop 2
	v_max_f32_e32 v156, v0, v0
	v_max_f32_e32 v2, v156, v2
	v_max_f32_e32 v156, v219, v221
	v_max_f32_e32 v3, v3, v3
	v_max_f32_e32 v157, v220, v220
	v_max_f32_e32 v3, v157, v3
	v_max3_f32 v3, v216, v218, v3
	v_max3_f32 v2, v2, v156, v3
	v_mov_b32_e32 v3, v2
	s_nop 1
	v_permlane16_swap_b32 v2, v3
	s_nop 1
	s_nop 0
	v_max_f32_e32 v2, v2, v3
	v_mov_b32_e32 v3, v2
	s_nop 1
	v_permlane32_swap_b32 v2, v3
	s_nop 1
	s_nop 0
	v_max3_f32 v3, v201, v2, v3
	v_cmp_gt_f32_e32 vcc, v3, v201
	s_cbranch_vccz .LBB0_377
	v_sub_f32_e32 v2, v201, v3
	v_mul_f32_e32 v2, v174, v2
	v_exp_f32_e32 v2, v2
	s_nop 0
	v_mul_f32_e32 v190, v190, v2
	v_pk_mul_f32 v[82:83], v[82:83], v[2:3] op_sel_hi:[1,0]
	v_pk_mul_f32 v[80:81], v[80:81], v[2:3] op_sel_hi:[1,0]
	v_pk_mul_f32 v[78:79], v[78:79], v[2:3] op_sel_hi:[1,0]
	v_pk_mul_f32 v[76:77], v[76:77], v[2:3] op_sel_hi:[1,0]
	v_pk_mul_f32 v[74:75], v[74:75], v[2:3] op_sel_hi:[1,0]
	v_pk_mul_f32 v[72:73], v[72:73], v[2:3] op_sel_hi:[1,0]
	v_pk_mul_f32 v[70:71], v[70:71], v[2:3] op_sel_hi:[1,0]
	v_pk_mul_f32 v[68:69], v[68:69], v[2:3] op_sel_hi:[1,0]
	s_branch .LBB0_378

; __device__ __forceinline__ float qmax(float x) { float a = x, b = x; swap16(a, b); a = fmaxf(a, b); b = a; swap32(a, b); return fmaxf(a, b); }
; __device__ __forceinline__ void softmax_pv(float& m, float& l, f32x4 (&o)[4], f32x4 s0, f32x4 s1, const bf16x8 (&vf)[4], float kL2e) {
;     float mx = fmaxf(fmaxf(fmaxf(s0[0], s0[1]), fmaxf(s0[2], s0[3])), fmaxf(fmaxf(s1[0], s1[1]), fmaxf(s1[2], s1[3])));
;     mx = qmax(mx);
;     const float mn = fmaxf(m, mx);
;     if (__builtin_amdgcn_ballot_w64(mn > m) != 0ull) {
;         const float alpha = __builtin_amdgcn_exp2f((m - mn) * kL2e);
;         l *= alpha;
; #pragma unroll
;         for (int dt = 0; dt < 4; ++dt) o[dt] = o[dt] * alpha;
;         m = mn;
.LBB0_382:
	v_max_f32_e32 v0, v0, v153
	v_max_f32_e32 v101, v155, v164
	v_max_f32_e32 v102, v165, v165
	v_max_f32_e32 v103, v163, v163
	v_max_f32_e32 v102, v103, v102
	v_max3_f32 v102, v152, v154, v102
	v_max3_f32 v0, v0, v101, v102
	v_mov_b32_e32 v101, v0
	s_nop 1
	v_permlane16_swap_b32 v0, v101
	s_nop 1
	s_nop 0
	v_max_f32_e32 v0, v0, v101
	v_mov_b32_e32 v101, v0
	s_nop 1
	v_permlane32_swap_b32 v0, v101
	s_nop 1
	s_nop 0
	v_max3_f32 v101, v199, v0, v101
	v_cmp_gt_f32_e32 vcc, v101, v199
	s_cbranch_vccz .LBB0_384
	v_sub_f32_e32 v0, v199, v101
	v_mul_f32_e32 v0, v174, v0
	v_exp_f32_e32 v0, v0
	s_nop 0
	v_mul_f32_e32 v177, v177, v0
	v_pk_mul_f32 v[66:67], v[66:67], v[0:1] op_sel_hi:[1,0]
	v_pk_mul_f32 v[64:65], v[64:65], v[0:1] op_sel_hi:[1,0]
	v_pk_mul_f32 v[62:63], v[62:63], v[0:1] op_sel_hi:[1,0]
	v_pk_mul_f32 v[60:61], v[60:61], v[0:1] op_sel_hi:[1,0]
	v_pk_mul_f32 v[58:59], v[58:59], v[0:1] op_sel_hi:[1,0]
	v_pk_mul_f32 v[56:57], v[56:57], v[0:1] op_sel_hi:[1,0]
	v_pk_mul_f32 v[54:55], v[54:55], v[0:1] op_sel_hi:[1,0]
	v_pk_mul_f32 v[52:53], v[52:53], v[0:1] op_sel_hi:[1,0]
	s_branch .LBB0_385

; __device__ __forceinline__ float qmax(float x) { float a = x, b = x; swap16(a, b); a = fmaxf(a, b); b = a; swap32(a, b); return fmaxf(a, b); }
; __device__ __forceinline__ void softmax_pv(float& m, float& l, f32x4 (&o)[4], f32x4 s0, f32x4 s1, const bf16x8 (&vf)[4], float kL2e) {
;     float mx = fmaxf(fmaxf(fmaxf(s0[0], s0[1]), fmaxf(s0[2], s0[3])), fmaxf(fmaxf(s1[0], s1[1]), fmaxf(s1[2], s1[3])));
;     mx = qmax(mx);
;     const float mn = fmaxf(m, mx);
;     if (__builtin_amdgcn_ballot_w64(mn > m) != 0ull) {
;         const float alpha = __builtin_amdgcn_exp2f((m - mn) * kL2e);
;         l *= alpha;
; #pragma unroll
;         for (int dt = 0; dt < 4; ++dt) o[dt] = o[dt] * alpha;
;         m = mn;
.LBB0_420:
	v_max_f32_e32 v0, v0, v117
	v_max_f32_e32 v93, v119, v125
	v_max_f32_e32 v94, v126, v126
	v_max_f32_e32 v95, v124, v124
	v_max_f32_e32 v94, v95, v94
	v_max3_f32 v94, v113, v118, v94
	v_max3_f32 v0, v0, v93, v94
	v_mov_b32_e32 v93, v0
	s_nop 1
	v_permlane16_swap_b32 v0, v93
	s_nop 1
	s_nop 0
	v_max_f32_e32 v0, v0, v93
	v_mov_b32_e32 v93, v0
	s_nop 1
	v_permlane32_swap_b32 v0, v93
	s_nop 1
	s_nop 0
	v_max3_f32 v93, v136, v0, v93
	v_cmp_gt_f32_e32 vcc, v93, v136
	s_cbranch_vccz .LBB0_422
	v_sub_f32_e32 v0, v136, v93
	v_mul_f32_e32 v0, v130, v0
	v_exp_f32_e32 v0, v0
	v_mov_b32_e32 v136, v93
	v_mul_f32_e32 v138, v138, v0
	v_pk_mul_f32 v[18:19], v[18:19], v[0:1] op_sel_hi:[1,0]
	v_pk_mul_f32 v[16:17], v[16:17], v[0:1] op_sel_hi:[1,0]
	v_pk_mul_f32 v[14:15], v[14:15], v[0:1] op_sel_hi:[1,0]
	v_pk_mul_f32 v[12:13], v[12:13], v[0:1] op_sel_hi:[1,0]
	v_pk_mul_f32 v[10:11], v[10:11], v[0:1] op_sel_hi:[1,0]
	v_pk_mul_f32 v[8:9], v[8:9], v[0:1] op_sel_hi:[1,0]
	v_pk_mul_f32 v[6:7], v[6:7], v[0:1] op_sel_hi:[1,0]
	v_pk_mul_f32 v[4:5], v[4:5], v[0:1] op_sel_hi:[1,0]
	s_branch .LBB0_423

; __device__ __forceinline__ float qmax(float x) { float a = x, b = x; swap16(a, b); a = fmaxf(a, b); b = a; swap32(a, b); return fmaxf(a, b); }
; __device__ __forceinline__ void softmax_pv(float& m, float& l, f32x4 (&o)[4], f32x4 s0, f32x4 s1, const bf16x8 (&vf)[4], float kL2e) {
;     float mx = fmaxf(fmaxf(fmaxf(s0[0], s0[1]), fmaxf(s0[2], s0[3])), fmaxf(fmaxf(s1[0], s1[1]), fmaxf(s1[2], s1[3])));
;     mx = qmax(mx);
;     const float mn = fmaxf(m, mx);
;     if (__builtin_amdgcn_ballot_w64(mn > m) != 0ull) {
;         const float alpha = __builtin_amdgcn_exp2f((m - mn) * kL2e);
;         l *= alpha;
; #pragma unroll
;         for (int dt = 0; dt < 4; ++dt) o[dt] = o[dt] * alpha;
;         m = mn;
.LBB0_428:
	v_max_f32_e32 v0, v0, v89
	v_max_f32_e32 v77, v91, v94
	v_max_f32_e32 v78, v95, v95
	v_max_f32_e32 v79, v93, v93
	v_max_f32_e32 v78, v79, v78
	v_max3_f32 v78, v88, v90, v78
	v_max3_f32 v0, v0, v77, v78
	v_mov_b32_e32 v77, v0
	s_nop 1
	v_permlane16_swap_b32 v0, v77
	s_nop 1
	s_nop 0
	v_max_f32_e32 v0, v0, v77
	v_mov_b32_e32 v77, v0
	s_nop 1
	v_permlane32_swap_b32 v0, v77
	s_nop 1
	s_nop 0
	v_max3_f32 v77, v136, v0, v77
	v_cmp_gt_f32_e32 vcc, v77, v136
	s_cbranch_vccz .LBB0_430
	v_sub_f32_e32 v0, v136, v77
	v_mul_f32_e32 v0, v130, v0
	v_exp_f32_e32 v0, v0
	v_mov_b32_e32 v136, v77
	v_mul_f32_e32 v92, v92, v0
	v_pk_mul_f32 v[18:19], v[18:19], v[0:1] op_sel_hi:[1,0]
	v_pk_mul_f32 v[16:17], v[16:17], v[0:1] op_sel_hi:[1,0]
	v_pk_mul_f32 v[14:15], v[14:15], v[0:1] op_sel_hi:[1,0]
	v_pk_mul_f32 v[12:13], v[12:13], v[0:1] op_sel_hi:[1,0]
	v_pk_mul_f32 v[10:11], v[10:11], v[0:1] op_sel_hi:[1,0]
	v_pk_mul_f32 v[8:9], v[8:9], v[0:1] op_sel_hi:[1,0]
	v_pk_mul_f32 v[6:7], v[6:7], v[0:1] op_sel_hi:[1,0]
	v_pk_mul_f32 v[4:5], v[4:5], v[0:1] op_sel_hi:[1,0]
	s_branch .LBB0_431

; __device__ __forceinline__ float qmax(float x) { float a = x, b = x; swap16(a, b); a = fmaxf(a, b); b = a; swap32(a, b); return fmaxf(a, b); }
; __device__ __forceinline__ void softmax_pv(float& m, float& l, f32x4 (&o)[4], f32x4 s0, f32x4 s1, const bf16x8 (&vf)[4], float kL2e) {
;     float mx = fmaxf(fmaxf(fmaxf(s0[0], s0[1]), fmaxf(s0[2], s0[3])), fmaxf(fmaxf(s1[0], s1[1]), fmaxf(s1[2], s1[3])));
;     mx = qmax(mx);
;     const float mn = fmaxf(m, mx);
;     if (__builtin_amdgcn_ballot_w64(mn > m) != 0ull) {
;         const float alpha = __builtin_amdgcn_exp2f((m - mn) * kL2e);
;         l *= alpha;
; #pragma unroll
;         for (int dt = 0; dt < 4; ++dt) o[dt] = o[dt] * alpha;
;         m = mn;
.LBB0_446:
	v_max_f32_e32 v0, v0, v3
	v_max_f32_e32 v109, v149, v151
	v_max_f32_e32 v110, v152, v152
	v_max_f32_e32 v111, v150, v150
	v_max_f32_e32 v110, v111, v110
	v_max3_f32 v110, v2, v129, v110
	v_max3_f32 v0, v0, v109, v110
	v_mov_b32_e32 v109, v0
	s_nop 1
	v_permlane16_swap_b32 v109, v0
	s_nop 1
	s_nop 0
	v_max_f32_e32 v0, v109, v0
	v_mov_b32_e32 v109, v0
	s_nop 1
	v_permlane32_swap_b32 v109, v0
	s_nop 1
	s_nop 0
	v_max3_f32 v109, v137, v109, v0
	v_cmp_gt_f32_e32 vcc, v109, v137
	s_cbranch_vccz .LBB0_448
	v_sub_f32_e32 v0, v137, v109
	v_mul_f32_e32 v0, v130, v0
	v_exp_f32_e32 v0, v0
	v_mov_b32_e32 v137, v109
	v_mul_f32_e32 v139, v139, v0
	v_pk_mul_f32 v[34:35], v[34:35], v[0:1] op_sel_hi:[1,0]
	v_pk_mul_f32 v[32:33], v[32:33], v[0:1] op_sel_hi:[1,0]
	v_pk_mul_f32 v[30:31], v[30:31], v[0:1] op_sel_hi:[1,0]
	v_pk_mul_f32 v[28:29], v[28:29], v[0:1] op_sel_hi:[1,0]
	v_pk_mul_f32 v[26:27], v[26:27], v[0:1] op_sel_hi:[1,0]
	v_pk_mul_f32 v[24:25], v[24:25], v[0:1] op_sel_hi:[1,0]
	v_pk_mul_f32 v[22:23], v[22:23], v[0:1] op_sel_hi:[1,0]
	v_pk_mul_f32 v[20:21], v[20:21], v[0:1] op_sel_hi:[1,0]
	s_branch .LBB0_449

; __device__ __forceinline__ float qmax(float x) { float a = x, b = x; swap16(a, b); a = fmaxf(a, b); b = a; swap32(a, b); return fmaxf(a, b); }
; __device__ __forceinline__ void softmax_pv(float& m, float& l, f32x4 (&o)[4], f32x4 s0, f32x4 s1, const bf16x8 (&vf)[4], float kL2e) {
;     float mx = fmaxf(fmaxf(fmaxf(s0[0], s0[1]), fmaxf(s0[2], s0[3])), fmaxf(fmaxf(s1[0], s1[1]), fmaxf(s1[2], s1[3])));
;     mx = qmax(mx);
;     const float mn = fmaxf(m, mx);
;     if (__builtin_amdgcn_ballot_w64(mn > m) != 0ull) {
;         const float alpha = __builtin_amdgcn_exp2f((m - mn) * kL2e);
;         l *= alpha;
; #pragma unroll
;         for (int dt = 0; dt < 4; ++dt) o[dt] = o[dt] * alpha;
;         m = mn;
.LBB0_454:
	v_max_f32_e32 v0, v0, v104
	v_max_f32_e32 v93, v106, v108
	v_max_f32_e32 v94, v109, v109
	v_max_f32_e32 v95, v107, v107
	v_max_f32_e32 v94, v95, v94
	v_max3_f32 v94, v3, v105, v94
	v_max3_f32 v0, v0, v93, v94
	v_mov_b32_e32 v93, v0
	s_nop 1
	v_permlane16_swap_b32 v0, v93
	s_nop 1
	s_nop 0
	v_max_f32_e32 v0, v0, v93
	v_mov_b32_e32 v93, v0
	s_nop 1
	v_permlane32_swap_b32 v0, v93
	s_nop 1
	s_nop 0
	v_max3_f32 v93, v137, v0, v93
	v_cmp_gt_f32_e32 vcc, v93, v137
	s_cbranch_vccz .LBB0_456
	v_sub_f32_e32 v0, v137, v93
	v_mul_f32_e32 v0, v130, v0
	v_exp_f32_e32 v0, v0
	v_mov_b32_e32 v137, v93
	v_mul_f32_e32 v139, v2, v0
	v_pk_mul_f32 v[34:35], v[34:35], v[0:1] op_sel_hi:[1,0]
	v_pk_mul_f32 v[32:33], v[32:33], v[0:1] op_sel_hi:[1,0]
	v_pk_mul_f32 v[30:31], v[30:31], v[0:1] op_sel_hi:[1,0]
	v_pk_mul_f32 v[28:29], v[28:29], v[0:1] op_sel_hi:[1,0]
	v_pk_mul_f32 v[26:27], v[26:27], v[0:1] op_sel_hi:[1,0]
	v_pk_mul_f32 v[24:25], v[24:25], v[0:1] op_sel_hi:[1,0]
	v_pk_mul_f32 v[22:23], v[22:23], v[0:1] op_sel_hi:[1,0]
	v_pk_mul_f32 v[20:21], v[20:21], v[0:1] op_sel_hi:[1,0]
	s_branch .LBB0_457

; __device__ __forceinline__ float qmax(float x) { float a = x, b = x; swap16(a, b); a = fmaxf(a, b); b = a; swap32(a, b); return fmaxf(a, b); }
; __device__ __forceinline__ void softmax_pv(float& m, float& l, f32x4 (&o)[4], f32x4 s0, f32x4 s1, const bf16x8 (&vf)[4], float kL2e) {
;     float mx = fmaxf(fmaxf(fmaxf(s0[0], s0[1]), fmaxf(s0[2], s0[3])), fmaxf(fmaxf(s1[0], s1[1]), fmaxf(s1[2], s1[3])));
;     mx = qmax(mx);
;     const float mn = fmaxf(m, mx);
;     if (__builtin_amdgcn_ballot_w64(mn > m) != 0ull) {
;         const float alpha = __builtin_amdgcn_exp2f((m - mn) * kL2e);
;         l *= alpha;
; #pragma unroll
;         for (int dt = 0; dt < 4; ++dt) o[dt] = o[dt] * alpha;
;         m = mn;
.LBB0_466:
	v_max_f32_e32 v0, v0, v152
	v_max_f32_e32 v117, v156, v177
	v_max_f32_e32 v118, v178, v178
	v_max_f32_e32 v119, v157, v157
	v_max_f32_e32 v118, v119, v118
	v_max3_f32 v118, v151, v153, v118
	v_max3_f32 v0, v0, v117, v118
	v_mov_b32_e32 v117, v0
	s_nop 1
	v_permlane16_swap_b32 v0, v117
	s_nop 1
	s_nop 0
	v_max_f32_e32 v0, v0, v117
	v_mov_b32_e32 v117, v0
	s_nop 1
	v_permlane32_swap_b32 v0, v117
	s_nop 1
	s_nop 0
	v_max3_f32 v117, v136, v0, v117
	v_cmp_gt_f32_e32 vcc, v117, v136
	s_cbranch_vccz .LBB0_468
	v_sub_f32_e32 v0, v136, v117
	v_mul_f32_e32 v0, v130, v0
	v_exp_f32_e32 v0, v0
	v_mov_b32_e32 v136, v117
	v_mul_f32_e32 v138, v138, v0
	v_pk_mul_f32 v[18:19], v[18:19], v[0:1] op_sel_hi:[1,0]
	v_pk_mul_f32 v[16:17], v[16:17], v[0:1] op_sel_hi:[1,0]
	v_pk_mul_f32 v[14:15], v[14:15], v[0:1] op_sel_hi:[1,0]
	v_pk_mul_f32 v[12:13], v[12:13], v[0:1] op_sel_hi:[1,0]
	v_pk_mul_f32 v[10:11], v[10:11], v[0:1] op_sel_hi:[1,0]
	v_pk_mul_f32 v[8:9], v[8:9], v[0:1] op_sel_hi:[1,0]
	v_pk_mul_f32 v[6:7], v[6:7], v[0:1] op_sel_hi:[1,0]
	v_pk_mul_f32 v[4:5], v[4:5], v[0:1] op_sel_hi:[1,0]
	s_branch .LBB0_469

; __device__ __forceinline__ float qmax(float x) { float a = x, b = x; swap16(a, b); a = fmaxf(a, b); b = a; swap32(a, b); return fmaxf(a, b); }
; __device__ __forceinline__ void softmax_pv(float& m, float& l, f32x4 (&o)[4], f32x4 s0, f32x4 s1, const bf16x8 (&vf)[4], float kL2e) {
;     float mx = fmaxf(fmaxf(fmaxf(s0[0], s0[1]), fmaxf(s0[2], s0[3])), fmaxf(fmaxf(s1[0], s1[1]), fmaxf(s1[2], s1[3])));
;     mx = qmax(mx);
;     const float mn = fmaxf(m, mx);
;     if (__builtin_amdgcn_ballot_w64(mn > m) != 0ull) {
;         const float alpha = __builtin_amdgcn_exp2f((m - mn) * kL2e);
;         l *= alpha;
; #pragma unroll
;         for (int dt = 0; dt < 4; ++dt) o[dt] = o[dt] * alpha;
;         m = mn;
;     }
;     const float mb = m * kL2e;
;     f32x4 p0, p1;
; #pragma unroll
;     for (int e = 0; e < 4; ++e) { p0[e] = __builtin_amdgcn_exp2f(s0[e] * kL2e - mb); p1[e] = __builtin_amdgcn_exp2f(s1[e] * kL2e - mb); }
;     l += ((p0[0] + p0[1]) + (p0[2] + p0[3])) + ((p1[0] + p1[1]) + (p1[2] + p1[3]));
.LBB0_473:
	s_nop 3
	v_pk_add_f32 v[118:119], v[150:151], v[154:155]
	v_pk_add_f32 v[120:121], v[152:153], v[156:157]
	v_max_f32_e32 v117, v178, v178
	v_pk_add_f32 v[118:119], v[118:119], v[120:121]
	v_max_f32_e32 v0, v0, v0
	v_pk_add_f32 v[118:119], v[118:119], v[118:119] op_sel:[0,1] op_sel_hi:[1,0]
	v_max_f32_e32 v0, v0, v117
	v_pk_add_f32 v[150:151], v[138:139], v[118:119]
	v_max_f32_e32 v117, v180, v182
	v_max_f32_e32 v118, v183, v183
	v_max_f32_e32 v119, v181, v181
	v_max_f32_e32 v118, v119, v118
	v_max3_f32 v118, v177, v179, v118
	v_max3_f32 v0, v0, v117, v118
	v_mov_b32_e32 v117, v0
	s_nop 1
	v_permlane16_swap_b32 v117, v0
	s_nop 1
	s_nop 0
	v_max_f32_e32 v0, v117, v0
	v_mov_b32_e32 v117, v0
	s_nop 1
	v_permlane32_swap_b32 v117, v0
	s_nop 1
	s_nop 0
	v_max3_f32 v117, v137, v117, v0
	v_cmp_gt_f32_e32 vcc, v117, v137
	s_cbranch_vccz .LBB0_475
	v_sub_f32_e32 v0, v137, v117
	v_mul_f32_e32 v0, v130, v0
	v_exp_f32_e32 v0, v0
	v_mov_b32_e32 v137, v117
	v_mul_f32_e32 v139, v139, v0
	v_pk_mul_f32 v[34:35], v[34:35], v[0:1] op_sel_hi:[1,0]
	v_pk_mul_f32 v[32:33], v[32:33], v[0:1] op_sel_hi:[1,0]
	v_pk_mul_f32 v[30:31], v[30:31], v[0:1] op_sel_hi:[1,0]
	v_pk_mul_f32 v[28:29], v[28:29], v[0:1] op_sel_hi:[1,0]
	v_pk_mul_f32 v[26:27], v[26:27], v[0:1] op_sel_hi:[1,0]
	v_pk_mul_f32 v[24:25], v[24:25], v[0:1] op_sel_hi:[1,0]
	v_pk_mul_f32 v[22:23], v[22:23], v[0:1] op_sel_hi:[1,0]
	v_pk_mul_f32 v[20:21], v[20:21], v[0:1] op_sel_hi:[1,0]
	s_branch .LBB0_476

; __device__ __forceinline__ float qmax(float x) { float a = x, b = x; swap16(a, b); a = fmaxf(a, b); b = a; swap32(a, b); return fmaxf(a, b); }
; __device__ __forceinline__ void softmax_pv(float& m, float& l, f32x4 (&o)[4], f32x4 s0, f32x4 s1, const bf16x8 (&vf)[4], float kL2e) {
;     float mx = fmaxf(fmaxf(fmaxf(s0[0], s0[1]), fmaxf(s0[2], s0[3])), fmaxf(fmaxf(s1[0], s1[1]), fmaxf(s1[2], s1[3])));
;     mx = qmax(mx);
;     const float mn = fmaxf(m, mx);
;     if (__builtin_amdgcn_ballot_w64(mn > m) != 0ull) {
;         const float alpha = __builtin_amdgcn_exp2f((m - mn) * kL2e);
;         l *= alpha;
; #pragma unroll
;         for (int dt = 0; dt < 4; ++dt) o[dt] = o[dt] * alpha;
;         m = mn;
.LBB0_481:
	v_max_f32_e32 v0, v0, v170
	v_max_f32_e32 v117, v172, v174
	v_max_f32_e32 v118, v175, v175
	v_max_f32_e32 v119, v173, v173
	v_max_f32_e32 v118, v119, v118
	v_max3_f32 v118, v167, v171, v118
	v_max3_f32 v0, v0, v117, v118
	v_mov_b32_e32 v117, v0
	s_nop 1
	v_permlane16_swap_b32 v0, v117
	s_nop 1
	s_nop 0
	v_max_f32_e32 v0, v0, v117
	v_mov_b32_e32 v117, v0
	s_nop 1
	v_permlane32_swap_b32 v0, v117
	s_nop 1
	s_nop 0
	v_max3_f32 v117, v136, v0, v117
	v_cmp_gt_f32_e32 vcc, v117, v136
	s_cbranch_vccz .LBB0_483
	v_sub_f32_e32 v0, v136, v117
	v_mul_f32_e32 v0, v130, v0
	v_exp_f32_e32 v0, v0
	v_mov_b32_e32 v136, v117
	v_mul_f32_e32 v150, v150, v0
	v_pk_mul_f32 v[18:19], v[18:19], v[0:1] op_sel_hi:[1,0]
	v_pk_mul_f32 v[16:17], v[16:17], v[0:1] op_sel_hi:[1,0]
	v_pk_mul_f32 v[14:15], v[14:15], v[0:1] op_sel_hi:[1,0]
	v_pk_mul_f32 v[12:13], v[12:13], v[0:1] op_sel_hi:[1,0]
	v_pk_mul_f32 v[10:11], v[10:11], v[0:1] op_sel_hi:[1,0]
	v_pk_mul_f32 v[8:9], v[8:9], v[0:1] op_sel_hi:[1,0]
	v_pk_mul_f32 v[6:7], v[6:7], v[0:1] op_sel_hi:[1,0]
	v_pk_mul_f32 v[4:5], v[4:5], v[0:1] op_sel_hi:[1,0]
	s_branch .LBB0_484

; __device__ __forceinline__ float qmax(float x) { float a = x, b = x; swap16(a, b); a = fmaxf(a, b); b = a; swap32(a, b); return fmaxf(a, b); }
; __device__ __forceinline__ void softmax_pv(float& m, float& l, f32x4 (&o)[4], f32x4 s0, f32x4 s1, const bf16x8 (&vf)[4], float kL2e) {
;     float mx = fmaxf(fmaxf(fmaxf(s0[0], s0[1]), fmaxf(s0[2], s0[3])), fmaxf(fmaxf(s1[0], s1[1]), fmaxf(s1[2], s1[3])));
;     mx = qmax(mx);
;     const float mn = fmaxf(m, mx);
;     if (__builtin_amdgcn_ballot_w64(mn > m) != 0ull) {
;         const float alpha = __builtin_amdgcn_exp2f((m - mn) * kL2e);
;         l *= alpha;
; #pragma unroll
;         for (int dt = 0; dt < 4; ++dt) o[dt] = o[dt] * alpha;
;         m = mn;
;     }
;     const float mb = m * kL2e;
;     f32x4 p0, p1;
; #pragma unroll
;     for (int e = 0; e < 4; ++e) { p0[e] = __builtin_amdgcn_exp2f(s0[e] * kL2e - mb); p1[e] = __builtin_amdgcn_exp2f(s1[e] * kL2e - mb); }
;     l += ((p0[0] + p0[1]) + (p0[2] + p0[3])) + ((p1[0] + p1[1]) + (p1[2] + p1[3]));
.LBB0_488:
	s_nop 3
	v_pk_add_f32 v[102:103], v[120:121], v[124:125]
	v_pk_add_f32 v[104:105], v[122:123], v[126:127]
	v_max_f32_e32 v101, v109, v109
	v_pk_add_f32 v[102:103], v[102:103], v[104:105]
	v_max_f32_e32 v0, v0, v0
	v_pk_add_f32 v[102:103], v[102:103], v[102:103] op_sel:[0,1] op_sel_hi:[1,0]
	v_max_f32_e32 v0, v0, v101
	v_pk_add_f32 v[138:139], v[150:151], v[102:103]
	v_max_f32_e32 v101, v111, v113
	v_max_f32_e32 v102, v114, v114
	v_max_f32_e32 v103, v112, v112
	v_max_f32_e32 v102, v103, v102
	v_max3_f32 v102, v108, v110, v102
	v_max3_f32 v0, v0, v101, v102
	v_mov_b32_e32 v101, v0
	s_nop 1
	v_permlane16_swap_b32 v101, v0
	s_nop 1
	s_nop 0
	v_max_f32_e32 v0, v101, v0
	v_mov_b32_e32 v101, v0
	s_nop 1
	v_permlane32_swap_b32 v101, v0
	s_nop 1
	s_nop 0
	v_max3_f32 v101, v137, v101, v0
	v_cmp_gt_f32_e32 vcc, v101, v137
	s_cbranch_vccz .LBB0_490
	v_sub_f32_e32 v0, v137, v101
	v_mul_f32_e32 v0, v130, v0
	v_exp_f32_e32 v0, v0
	v_mov_b32_e32 v137, v101
	v_mul_f32_e32 v151, v151, v0
	v_pk_mul_f32 v[34:35], v[34:35], v[0:1] op_sel_hi:[1,0]
	v_pk_mul_f32 v[32:33], v[32:33], v[0:1] op_sel_hi:[1,0]
	v_pk_mul_f32 v[30:31], v[30:31], v[0:1] op_sel_hi:[1,0]
	v_pk_mul_f32 v[28:29], v[28:29], v[0:1] op_sel_hi:[1,0]
	v_pk_mul_f32 v[26:27], v[26:27], v[0:1] op_sel_hi:[1,0]
	v_pk_mul_f32 v[24:25], v[24:25], v[0:1] op_sel_hi:[1,0]
	v_pk_mul_f32 v[22:23], v[22:23], v[0:1] op_sel_hi:[1,0]
	v_pk_mul_f32 v[20:21], v[20:21], v[0:1] op_sel_hi:[1,0]
	s_branch .LBB0_491

; __device__ __forceinline__ float qmax(float x) { float a = x, b = x; swap16(a, b); a = fmaxf(a, b); b = a; swap32(a, b); return fmaxf(a, b); }
; __device__ __forceinline__ void softmax_pv(float& m, float& l, f32x4 (&o)[4], f32x4 s0, f32x4 s1, const bf16x8 (&vf)[4], float kL2e) {
;     float mx = fmaxf(fmaxf(fmaxf(s0[0], s0[1]), fmaxf(s0[2], s0[3])), fmaxf(fmaxf(s1[0], s1[1]), fmaxf(s1[2], s1[3])));
;     mx = qmax(mx);
;     const float mn = fmaxf(m, mx);
;     if (__builtin_amdgcn_ballot_w64(mn > m) != 0ull) {
;         const float alpha = __builtin_amdgcn_exp2f((m - mn) * kL2e);
;         l *= alpha;
; #pragma unroll
;         for (int dt = 0; dt < 4; ++dt) o[dt] = o[dt] * alpha;
;         m = mn;
;     }
;     const float mb = m * kL2e;
;     f32x4 p0, p1;
; #pragma unroll
;     for (int e = 0; e < 4; ++e) { p0[e] = __builtin_amdgcn_exp2f(s0[e] * kL2e - mb); p1[e] = __builtin_amdgcn_exp2f(s1[e] * kL2e - mb); }
;     l += ((p0[0] + p0[1]) + (p0[2] + p0[3])) + ((p1[0] + p1[1]) + (p1[2] + p1[3]));
.LBB0_494:
	v_pk_add_f32 v[2:3], v[2:3], v[90:91]
	s_nop 2
	v_pk_add_f32 v[70:71], v[88:89], v[92:93]
	v_max_f32_e32 v0, v0, v0
	v_pk_add_f32 v[2:3], v[2:3], v[70:71]
	v_max_f32_e32 v69, v79, v79
	v_pk_add_f32 v[2:3], v[2:3], v[2:3] op_sel:[0,1] op_sel_hi:[1,0]
	v_max_f32_e32 v70, v80, v80
	v_pk_add_f32 v[2:3], v[138:139], v[2:3]
	s_nop 0
	v_max_f32_e32 v3, v77, v77
	v_max_f32_e32 v0, v0, v3
	v_max_f32_e32 v3, v81, v81
	v_max_f32_e32 v3, v69, v3
	v_max_f32_e32 v69, v82, v82
	v_max_f32_e32 v69, v70, v69
	v_max3_f32 v69, v76, v78, v69
	v_max3_f32 v0, v0, v3, v69
	v_mov_b32_e32 v3, v0
	s_nop 1
	v_permlane16_swap_b32 v0, v3
	s_nop 1
	s_nop 0
	v_max_f32_e32 v0, v0, v3
	v_mov_b32_e32 v3, v0
	s_nop 1
	v_permlane32_swap_b32 v0, v3
	s_nop 1
	s_nop 0
	v_max3_f32 v69, v137, v0, v3
	v_cmp_gt_f32_e32 vcc, v69, v137
	s_cbranch_vccz .LBB0_503
	v_sub_f32_e32 v0, v137, v69
	v_mul_f32_e32 v0, v130, v0
	v_exp_f32_e32 v0, v0
	v_mov_b32_e32 v137, v69
	v_mul_f32_e32 v139, v139, v0
	v_pk_mul_f32 v[34:35], v[34:35], v[0:1] op_sel_hi:[1,0]
	v_pk_mul_f32 v[32:33], v[32:33], v[0:1] op_sel_hi:[1,0]
	v_pk_mul_f32 v[30:31], v[30:31], v[0:1] op_sel_hi:[1,0]
	v_pk_mul_f32 v[28:29], v[28:29], v[0:1] op_sel_hi:[1,0]
	v_pk_mul_f32 v[26:27], v[26:27], v[0:1] op_sel_hi:[1,0]
	v_pk_mul_f32 v[24:25], v[24:25], v[0:1] op_sel_hi:[1,0]
	v_pk_mul_f32 v[22:23], v[22:23], v[0:1] op_sel_hi:[1,0]
	v_pk_mul_f32 v[20:21], v[20:21], v[0:1] op_sel_hi:[1,0]

; __device__ __forceinline__ float qmax(float x) { float a = x, b = x; swap16(a, b); a = fmaxf(a, b); b = a; swap32(a, b); return fmaxf(a, b); }
; __device__ __forceinline__ void softmax_pv(float& m, float& l, f32x4 (&o)[4], f32x4 s0, f32x4 s1, const bf16x8 (&vf)[4], float kL2e) {
;     float mx = fmaxf(fmaxf(fmaxf(s0[0], s0[1]), fmaxf(s0[2], s0[3])), fmaxf(fmaxf(s1[0], s1[1]), fmaxf(s1[2], s1[3])));
;     mx = qmax(mx);
;     const float mn = fmaxf(m, mx);
;     if (__builtin_amdgcn_ballot_w64(mn > m) != 0ull) {
;         const float alpha = __builtin_amdgcn_exp2f((m - mn) * kL2e);
;         l *= alpha;
; #pragma unroll
;         for (int dt = 0; dt < 4; ++dt) o[dt] = o[dt] * alpha;
;         m = mn;
.LBB0_501:
	v_max_f32_e32 v0, v0, v111
	v_max_f32_e32 v2, v113, v115
	v_max_f32_e32 v85, v116, v116
	v_max_f32_e32 v86, v114, v114
	v_max_f32_e32 v85, v86, v85
	v_max3_f32 v85, v3, v112, v85
	v_max3_f32 v0, v0, v2, v85
	v_mov_b32_e32 v2, v0
	s_nop 1
	v_permlane16_swap_b32 v2, v0
	s_nop 1
	s_nop 0
	v_max_f32_e32 v0, v2, v0
	v_mov_b32_e32 v2, v0
	s_nop 1
	v_permlane32_swap_b32 v2, v0
	s_nop 1
	s_nop 0
	v_max3_f32 v85, v136, v2, v0
	v_cmp_gt_f32_e32 vcc, v85, v136
	s_cbranch_vccz .LBB0_504
	v_sub_f32_e32 v0, v136, v85
	v_mul_f32_e32 v0, v130, v0
	v_exp_f32_e32 v0, v0
	v_mov_b32_e32 v136, v85
	v_mul_f32_e32 v138, v138, v0
	v_pk_mul_f32 v[18:19], v[18:19], v[0:1] op_sel_hi:[1,0]
	v_pk_mul_f32 v[16:17], v[16:17], v[0:1] op_sel_hi:[1,0]
	v_pk_mul_f32 v[14:15], v[14:15], v[0:1] op_sel_hi:[1,0]
	v_pk_mul_f32 v[12:13], v[12:13], v[0:1] op_sel_hi:[1,0]
	v_pk_mul_f32 v[10:11], v[10:11], v[0:1] op_sel_hi:[1,0]
	v_pk_mul_f32 v[8:9], v[8:9], v[0:1] op_sel_hi:[1,0]
	v_pk_mul_f32 v[6:7], v[6:7], v[0:1] op_sel_hi:[1,0]
	v_pk_mul_f32 v[4:5], v[4:5], v[0:1] op_sel_hi:[1,0]
	s_branch .LBB0_505

; __device__ __forceinline__ float qmax(float x) { float a = x, b = x; swap16(a, b); a = fmaxf(a, b); b = a; swap32(a, b); return fmaxf(a, b); }
; __device__ __forceinline__ void softmax_pv(float& m, float& l, f32x4 (&o)[4], f32x4 s0, f32x4 s1, const bf16x8 (&vf)[4], float kL2e) {
;     float mx = fmaxf(fmaxf(fmaxf(s0[0], s0[1]), fmaxf(s0[2], s0[3])), fmaxf(fmaxf(s1[0], s1[1]), fmaxf(s1[2], s1[3])));
;     mx = qmax(mx);
;     const float mn = fmaxf(m, mx);
;     if (__builtin_amdgcn_ballot_w64(mn > m) != 0ull) {
;         const float alpha = __builtin_amdgcn_exp2f((m - mn) * kL2e);
;         l *= alpha;
; #pragma unroll
;         for (int dt = 0; dt < 4; ++dt) o[dt] = o[dt] * alpha;
;         m = mn;
.LBB0_512:
	v_max_f32_e32 v153, v162, v150
	v_max_f32_e32 v158, v151, v152
	v_max_f32_e32 v159, v157, v157
	v_max_f32_e32 v160, v156, v156
	v_max_f32_e32 v159, v160, v159
	v_max3_f32 v159, v154, v155, v159
	v_max3_f32 v153, v153, v158, v159
	v_mov_b32_e32 v158, v153
	s_nop 1
	v_permlane16_swap_b32 v158, v153
	s_nop 1
	s_nop 0
	v_max_f32_e32 v153, v158, v153
	v_mov_b32_e32 v158, v153
	s_nop 1
	v_permlane32_swap_b32 v158, v153
	s_nop 1
	s_nop 0
	v_max3_f32 v163, v202, v158, v153
	v_cmp_gt_f32_e32 vcc, v163, v202
	s_cbranch_vccz .LBB0_620
	v_sub_f32_e32 v153, v202, v163
	v_mul_f32_e32 v153, v20, v153
	v_exp_f32_e32 v158, v153
	s_nop 0
	v_mul_f32_e32 v18, v18, v158
	v_pk_mul_f32 v[16:17], v[16:17], v[158:159] op_sel_hi:[1,0]
	v_pk_mul_f32 v[14:15], v[14:15], v[158:159] op_sel_hi:[1,0]
	v_pk_mul_f32 v[12:13], v[12:13], v[158:159] op_sel_hi:[1,0]
	v_pk_mul_f32 v[10:11], v[10:11], v[158:159] op_sel_hi:[1,0]
	v_pk_mul_f32 v[8:9], v[8:9], v[158:159] op_sel_hi:[1,0]
	v_pk_mul_f32 v[6:7], v[6:7], v[158:159] op_sel_hi:[1,0]
	v_pk_mul_f32 v[4:5], v[4:5], v[158:159] op_sel_hi:[1,0]
	v_pk_mul_f32 v[2:3], v[2:3], v[158:159] op_sel_hi:[1,0]

; __device__ __forceinline__ float qmax(float x) { float a = x, b = x; swap16(a, b); a = fmaxf(a, b); b = a; swap32(a, b); return fmaxf(a, b); }
; __device__ __forceinline__ void softmax_pv(float& m, float& l, f32x4 (&o)[4], f32x4 s0, f32x4 s1, const bf16x8 (&vf)[4], float kL2e) {
;     float mx = fmaxf(fmaxf(fmaxf(s0[0], s0[1]), fmaxf(s0[2], s0[3])), fmaxf(fmaxf(s1[0], s1[1]), fmaxf(s1[2], s1[3])));
;     mx = qmax(mx);
;     const float mn = fmaxf(m, mx);
;     if (__builtin_amdgcn_ballot_w64(mn > m) != 0ull) {
;         const float alpha = __builtin_amdgcn_exp2f((m - mn) * kL2e);
;         l *= alpha;
; #pragma unroll
;         for (int dt = 0; dt < 4; ++dt) o[dt] = o[dt] * alpha;
;         m = mn;
.LBB0_516:
	s_add_i32 s48, s49, 1
	s_min_i32 s22, s48, s31
	s_add_i32 s22, s22, s1
	s_lshl_b32 s22, s22, 6
	s_add_i32 s22, s22, s30
	s_waitcnt vmcnt(3)
	v_mad_i64_i32 v[134:135], s[24:25], s22, v242, v[182:183]
	s_movk_i32 s24, 0x5000
	s_ashr_i32 s23, s22, 31
	global_load_dwordx4 v[150:153], v[134:135], off
	global_load_dwordx4 v[154:157], v[134:135], off offset:64
	v_add_co_u32_e32 v134, vcc, s24, v134
	s_waitcnt vmcnt(2)
	v_lshl_add_u64 v[142:143], s[22:23], 1, v[184:185]
	v_addc_co_u32_e32 v135, vcc, 0, v135, vcc
	v_add_co_u32_e32 v138, vcc, s45, v142
	global_load_dwordx4 v[162:165], v[134:135], off offset:2048
	global_load_dwordx4 v[158:161], v[134:135], off offset:2112
	v_addc_co_u32_e32 v139, vcc, 0, v143, vcc
	v_add_co_u32_e32 v144, vcc, 0x121000, v142
	global_load_dwordx4 v[134:137], v[142:143], off
	s_nop 0
	global_load_dwordx4 v[138:141], v[138:139], off offset:2048
	v_addc_co_u32_e32 v145, vcc, 0, v143, vcc
	v_add_co_u32_e32 v142, vcc, 0x1b1000, v142
	s_cmp_lt_u32 s49, 8
	s_nop 0
	v_addc_co_u32_e32 v143, vcc, 0, v143, vcc
	global_load_dwordx4 v[146:149], v[144:145], off
	s_nop 0
	global_load_dwordx4 v[142:145], v[142:143], off offset:2048
	s_cselect_b64 s[22:23], -1, 0
	s_cmp_gt_u32 s49, 7
	s_cbranch_scc1 .LBB0_537
	s_waitcnt vmcnt(8)
	v_mfma_f32_16x16x32_bf16 v[166:169], v[102:105], v[82:85], 0
	v_mov_b32_e32 v186, v19
	v_mfma_f32_16x16x32_bf16 v[170:173], v[106:109], v[78:81], v[166:169]
	v_mfma_f32_16x16x32_bf16 v[166:169], v[110:113], v[82:85], 0
	v_mfma_f32_16x16x32_bf16 v[166:169], v[114:117], v[78:81], v[166:169]
	v_add_u32_e32 v210, s43, v198
	v_add_u32_e32 v211, s43, v197
	v_add_u32_e32 v212, s43, v196
	v_add_u32_e32 v213, s43, v195
	v_add_u32_e32 v214, s43, v194
	v_add_u32_e32 v215, s43, v193
	v_add_u32_e32 v216, s43, v192
	v_add_u32_e32 v217, s43, v191
	ds_read_b32 v210, v210 offset:868
	ds_read_b32 v211, v211 offset:868
	ds_read_b32 v212, v212 offset:868
	ds_read_b32 v213, v213 offset:868
	ds_read_b32 v214, v214 offset:868
	ds_read_b32 v215, v215 offset:868
	ds_read_b32 v216, v216 offset:868
	ds_read_b32 v217, v217 offset:868
	s_waitcnt lgkmcnt(0)
	v_add_f32_e32 v210, v170, v210
	v_add_f32_e32 v211, v166, v211
	v_add_f32_e32 v212, v171, v212
	v_add_f32_e32 v213, v167, v213
	v_add_f32_e32 v214, v172, v214
	v_add_f32_e32 v215, v168, v215
	v_add_f32_e32 v216, v173, v216
	v_add_f32_e32 v217, v169, v217
	v_cndmask_b32_e64 v186, v19, v210, s[6:7]
	v_cndmask_b32_e64 v170, v19, v211, s[8:9]
	v_cndmask_b32_e64 v166, v19, v212, s[10:11]
	v_cndmask_b32_e64 v171, v19, v213, s[14:15]
	v_cndmask_b32_e64 v167, v19, v214, s[16:17]
	v_cndmask_b32_e64 v172, v19, v215, s[18:19]
	v_cndmask_b32_e64 v168, v19, v216, s[20:21]
	v_cndmask_b32_e64 v173, v19, v217, s[2:3]
	v_max_f32_e32 v169, v186, v166
	v_max_f32_e32 v187, v167, v168
	v_max_f32_e32 v203, v173, v173
	v_max_f32_e32 v204, v172, v172
	v_max_f32_e32 v203, v204, v203
	v_max3_f32 v203, v170, v171, v203
	v_max3_f32 v169, v169, v187, v203
	v_mov_b32_e32 v187, v169
	s_nop 1
	v_permlane16_swap_b32 v169, v187
	s_nop 1
	s_nop 0
	v_max_f32_e32 v169, v169, v187
	v_mov_b32_e32 v187, v169
	s_nop 1
	v_permlane32_swap_b32 v169, v187
	s_nop 1
	s_nop 0
	v_max3_f32 v187, v199, v169, v187
	v_cmp_gt_f32_e32 vcc, v187, v199
	s_cbranch_vccz .LBB0_535
	v_sub_f32_e32 v169, v199, v187
	v_mul_f32_e32 v169, v20, v169
	v_exp_f32_e32 v204, v169
	s_nop 0
	v_mul_f32_e32 v190, v190, v204
	v_pk_mul_f32 v[100:101], v[100:101], v[204:205] op_sel_hi:[1,0]
	v_pk_mul_f32 v[98:99], v[98:99], v[204:205] op_sel_hi:[1,0]
	v_pk_mul_f32 v[96:97], v[96:97], v[204:205] op_sel_hi:[1,0]
	v_pk_mul_f32 v[94:95], v[94:95], v[204:205] op_sel_hi:[1,0]
	v_pk_mul_f32 v[92:93], v[92:93], v[204:205] op_sel_hi:[1,0]
	v_pk_mul_f32 v[90:91], v[90:91], v[204:205] op_sel_hi:[1,0]
	v_pk_mul_f32 v[88:89], v[88:89], v[204:205] op_sel_hi:[1,0]
	v_pk_mul_f32 v[86:87], v[86:87], v[204:205] op_sel_hi:[1,0]
	s_branch .LBB0_536

; __device__ __forceinline__ float qmax(float x) { float a = x, b = x; swap16(a, b); a = fmaxf(a, b); b = a; swap32(a, b); return fmaxf(a, b); }
; __device__ __forceinline__ void softmax_pv(float& m, float& l, f32x4 (&o)[4], f32x4 s0, f32x4 s1, const bf16x8 (&vf)[4], float kL2e) {
;     float mx = fmaxf(fmaxf(fmaxf(s0[0], s0[1]), fmaxf(s0[2], s0[3])), fmaxf(fmaxf(s1[0], s1[1]), fmaxf(s1[2], s1[3])));
;     mx = qmax(mx);
;     const float mn = fmaxf(m, mx);
;     if (__builtin_amdgcn_ballot_w64(mn > m) != 0ull) {
;         const float alpha = __builtin_amdgcn_exp2f((m - mn) * kL2e);
;         l *= alpha;
; #pragma unroll
;         for (int dt = 0; dt < 4; ++dt) o[dt] = o[dt] * alpha;
;         m = mn;
.LBB0_537:
	s_add_i32 s50, s1, s49
	s_cmp_ge_u32 s50, s27
	s_cselect_b64 s[24:25], -1, 0
	s_cmp_lt_u32 s50, s34
	s_cselect_b64 s[56:57], -1, 0
	s_and_b64 s[24:25], s[24:25], s[56:57]
	s_andn2_b64 vcc, exec, s[24:25]
	s_cbranch_vccnz .LBB0_558
	s_waitcnt vmcnt(8)
	v_mfma_f32_16x16x32_bf16 v[166:169], v[102:105], v[74:77], 0
	v_mov_b32_e32 v186, v19
	v_mfma_f32_16x16x32_bf16 v[170:173], v[106:109], v[70:73], v[166:169]
	v_mfma_f32_16x16x32_bf16 v[166:169], v[110:113], v[74:77], 0
	v_mfma_f32_16x16x32_bf16 v[166:169], v[114:117], v[70:73], v[166:169]
	v_add_u32_e32 v210, s43, v198
	v_add_u32_e32 v211, s43, v197
	v_add_u32_e32 v212, s43, v196
	v_add_u32_e32 v213, s43, v195
	v_add_u32_e32 v214, s43, v194
	v_add_u32_e32 v215, s43, v193
	v_add_u32_e32 v216, s43, v192
	v_add_u32_e32 v217, s43, v191
	ds_read_b32 v210, v210 offset:744
	ds_read_b32 v211, v211 offset:744
	ds_read_b32 v212, v212 offset:744
	ds_read_b32 v213, v213 offset:744
	ds_read_b32 v214, v214 offset:744
	ds_read_b32 v215, v215 offset:744
	ds_read_b32 v216, v216 offset:744
	ds_read_b32 v217, v217 offset:744
	s_waitcnt lgkmcnt(0)
	v_add_f32_e32 v210, v170, v210
	v_add_f32_e32 v211, v166, v211
	v_add_f32_e32 v212, v171, v212
	v_add_f32_e32 v213, v167, v213
	v_add_f32_e32 v214, v172, v214
	v_add_f32_e32 v215, v168, v215
	v_add_f32_e32 v216, v173, v216
	v_add_f32_e32 v217, v169, v217
	v_cndmask_b32_e64 v186, v19, v210, s[6:7]
	v_cndmask_b32_e64 v170, v19, v211, s[8:9]
	v_cndmask_b32_e64 v166, v19, v212, s[10:11]
	v_cndmask_b32_e64 v171, v19, v213, s[14:15]
	v_cndmask_b32_e64 v167, v19, v214, s[16:17]
	v_cndmask_b32_e64 v172, v19, v215, s[18:19]
	v_cndmask_b32_e64 v168, v19, v216, s[20:21]
	v_cndmask_b32_e64 v173, v19, v217, s[2:3]
	v_max_f32_e32 v169, v186, v166
	v_max_f32_e32 v187, v167, v168
	v_max_f32_e32 v203, v173, v173
	v_max_f32_e32 v204, v172, v172
	v_max_f32_e32 v203, v204, v203
	v_max3_f32 v203, v170, v171, v203
	v_max3_f32 v169, v169, v187, v203
	v_mov_b32_e32 v187, v169
	s_nop 1
	v_permlane16_swap_b32 v169, v187
	s_nop 1
	s_nop 0
	v_max_f32_e32 v169, v169, v187
	v_mov_b32_e32 v187, v169
	s_nop 1
	v_permlane32_swap_b32 v169, v187
	s_nop 1
	s_nop 0
	v_max3_f32 v187, v200, v169, v187
	v_cmp_gt_f32_e32 vcc, v187, v200
	s_cbranch_vccz .LBB0_556
	v_sub_f32_e32 v169, v200, v187
	v_mul_f32_e32 v169, v20, v169
	v_exp_f32_e32 v200, v169
	s_nop 0
	v_mul_f32_e32 v189, v189, v200
	v_pk_mul_f32 v[68:69], v[68:69], v[200:201] op_sel_hi:[1,0]
	v_pk_mul_f32 v[66:67], v[66:67], v[200:201] op_sel_hi:[1,0]
	v_pk_mul_f32 v[56:57], v[56:57], v[200:201] op_sel_hi:[1,0]
	v_pk_mul_f32 v[54:55], v[54:55], v[200:201] op_sel_hi:[1,0]
	v_pk_mul_f32 v[48:49], v[48:49], v[200:201] op_sel_hi:[1,0]
	v_pk_mul_f32 v[46:47], v[46:47], v[200:201] op_sel_hi:[1,0]
	v_pk_mul_f32 v[40:41], v[40:41], v[200:201] op_sel_hi:[1,0]
	v_pk_mul_f32 v[38:39], v[38:39], v[200:201] op_sel_hi:[1,0]
	s_branch .LBB0_557

; __device__ __forceinline__ float qmax(float x) { float a = x, b = x; swap16(a, b); a = fmaxf(a, b); b = a; swap32(a, b); return fmaxf(a, b); }
; __device__ __forceinline__ void softmax_pv(float& m, float& l, f32x4 (&o)[4], f32x4 s0, f32x4 s1, const bf16x8 (&vf)[4], float kL2e) {
;     float mx = fmaxf(fmaxf(fmaxf(s0[0], s0[1]), fmaxf(s0[2], s0[3])), fmaxf(fmaxf(s1[0], s1[1]), fmaxf(s1[2], s1[3])));
;     mx = qmax(mx);
;     const float mn = fmaxf(m, mx);
;     if (__builtin_amdgcn_ballot_w64(mn > m) != 0ull) {
;         const float alpha = __builtin_amdgcn_exp2f((m - mn) * kL2e);
;         l *= alpha;
; #pragma unroll
;         for (int dt = 0; dt < 4; ++dt) o[dt] = o[dt] * alpha;
;         m = mn;
.LBB0_558:
	s_cmp_ge_u32 s50, s28
	s_cselect_b64 s[24:25], -1, 0
	s_cmp_lt_u32 s50, s35
	s_cselect_b64 s[56:57], -1, 0
	s_and_b64 s[24:25], s[24:25], s[56:57]
	s_andn2_b64 vcc, exec, s[24:25]
	s_cbranch_vccnz .LBB0_579
	s_waitcnt vmcnt(8)
	v_mfma_f32_16x16x32_bf16 v[166:169], v[102:105], v[62:65], 0
	v_mov_b32_e32 v186, v19
	v_mfma_f32_16x16x32_bf16 v[170:173], v[106:109], v[58:61], v[166:169]
	v_mfma_f32_16x16x32_bf16 v[166:169], v[110:113], v[62:65], 0
	v_mfma_f32_16x16x32_bf16 v[166:169], v[114:117], v[58:61], v[166:169]
	v_add_u32_e32 v210, s43, v198
	v_add_u32_e32 v211, s43, v197
	v_add_u32_e32 v212, s43, v196
	v_add_u32_e32 v213, s43, v195
	v_add_u32_e32 v214, s43, v194
	v_add_u32_e32 v215, s43, v193
	v_add_u32_e32 v216, s43, v192
	v_add_u32_e32 v217, s43, v191
	ds_read_b32 v210, v210 offset:620
	ds_read_b32 v211, v211 offset:620
	ds_read_b32 v212, v212 offset:620
	ds_read_b32 v213, v213 offset:620
	ds_read_b32 v214, v214 offset:620
	ds_read_b32 v215, v215 offset:620
	ds_read_b32 v216, v216 offset:620
	ds_read_b32 v217, v217 offset:620
	s_waitcnt lgkmcnt(0)
	v_add_f32_e32 v210, v170, v210
	v_add_f32_e32 v211, v166, v211
	v_add_f32_e32 v212, v171, v212
	v_add_f32_e32 v213, v167, v213
	v_add_f32_e32 v214, v172, v214
	v_add_f32_e32 v215, v168, v215
	v_add_f32_e32 v216, v173, v216
	v_add_f32_e32 v217, v169, v217
	v_cndmask_b32_e64 v186, v19, v210, s[6:7]
	v_cndmask_b32_e64 v170, v19, v211, s[8:9]
	v_cndmask_b32_e64 v166, v19, v212, s[10:11]
	v_cndmask_b32_e64 v171, v19, v213, s[14:15]
	v_cndmask_b32_e64 v167, v19, v214, s[16:17]
	v_cndmask_b32_e64 v172, v19, v215, s[18:19]
	v_cndmask_b32_e64 v168, v19, v216, s[20:21]
	v_cndmask_b32_e64 v173, v19, v217, s[2:3]
	v_max_f32_e32 v169, v186, v166
	v_max_f32_e32 v187, v167, v168
	v_max_f32_e32 v203, v173, v173
	v_max_f32_e32 v204, v172, v172
	v_max_f32_e32 v203, v204, v203
	v_max3_f32 v203, v170, v171, v203
	v_max3_f32 v169, v169, v187, v203
	v_mov_b32_e32 v187, v169
	s_nop 1
	v_permlane16_swap_b32 v187, v169
	s_nop 1
	s_nop 0
	v_max_f32_e32 v169, v187, v169
	v_mov_b32_e32 v187, v169
	s_nop 1
	v_permlane32_swap_b32 v187, v169
	s_nop 1
	s_nop 0
	v_max3_f32 v187, v201, v187, v169
	v_cmp_gt_f32_e32 vcc, v187, v201
	s_cbranch_vccz .LBB0_577
	v_sub_f32_e32 v169, v201, v187
	v_mul_f32_e32 v169, v20, v169
	v_exp_f32_e32 v204, v169
	s_nop 0
	v_mul_f32_e32 v0, v0, v204
	v_pk_mul_f32 v[36:37], v[36:37], v[204:205] op_sel_hi:[1,0]
	v_pk_mul_f32 v[34:35], v[34:35], v[204:205] op_sel_hi:[1,0]
	v_pk_mul_f32 v[32:33], v[32:33], v[204:205] op_sel_hi:[1,0]
	v_pk_mul_f32 v[30:31], v[30:31], v[204:205] op_sel_hi:[1,0]
	v_pk_mul_f32 v[28:29], v[28:29], v[204:205] op_sel_hi:[1,0]
	v_pk_mul_f32 v[26:27], v[26:27], v[204:205] op_sel_hi:[1,0]
	v_pk_mul_f32 v[24:25], v[24:25], v[204:205] op_sel_hi:[1,0]
	v_pk_mul_f32 v[22:23], v[22:23], v[204:205] op_sel_hi:[1,0]
	s_branch .LBB0_578

; __device__ __forceinline__ float qmax(float x) { float a = x, b = x; swap16(a, b); a = fmaxf(a, b); b = a; swap32(a, b); return fmaxf(a, b); }
; __device__ __forceinline__ void softmax_pv(float& m, float& l, f32x4 (&o)[4], f32x4 s0, f32x4 s1, const bf16x8 (&vf)[4], float kL2e) {
;     float mx = fmaxf(fmaxf(fmaxf(s0[0], s0[1]), fmaxf(s0[2], s0[3])), fmaxf(fmaxf(s1[0], s1[1]), fmaxf(s1[2], s1[3])));
;     mx = qmax(mx);
;     const float mn = fmaxf(m, mx);
;     if (__builtin_amdgcn_ballot_w64(mn > m) != 0ull) {
;         const float alpha = __builtin_amdgcn_exp2f((m - mn) * kL2e);
;         l *= alpha;
; #pragma unroll
;         for (int dt = 0; dt < 4; ++dt) o[dt] = o[dt] * alpha;
;         m = mn;
.LBB0_579:
	s_cmp_ge_u32 s50, s26
	s_cselect_b64 s[24:25], -1, 0
	s_cmp_lt_u32 s50, s42
	s_cselect_b64 s[56:57], -1, 0
	s_and_b64 s[24:25], s[24:25], s[56:57]
	s_andn2_b64 vcc, exec, s[24:25]
	s_cbranch_vccnz .LBB0_600
	s_waitcnt vmcnt(8)
	v_mfma_f32_16x16x32_bf16 v[166:169], v[102:105], v[50:53], 0
	v_mov_b32_e32 v186, v19
	v_mfma_f32_16x16x32_bf16 v[170:173], v[106:109], v[42:45], v[166:169]
	v_mfma_f32_16x16x32_bf16 v[166:169], v[110:113], v[50:53], 0
	v_mfma_f32_16x16x32_bf16 v[166:169], v[114:117], v[42:45], v[166:169]
	v_add_u32_e32 v210, s43, v198
	v_add_u32_e32 v211, s43, v197
	v_add_u32_e32 v212, s43, v196
	v_add_u32_e32 v213, s43, v195
	v_add_u32_e32 v214, s43, v194
	v_add_u32_e32 v215, s43, v193
	v_add_u32_e32 v216, s43, v192
	v_add_u32_e32 v217, s43, v191
	ds_read_b32 v210, v210 offset:496
	ds_read_b32 v211, v211 offset:496
	ds_read_b32 v212, v212 offset:496
	ds_read_b32 v213, v213 offset:496
	ds_read_b32 v214, v214 offset:496
	ds_read_b32 v215, v215 offset:496
	ds_read_b32 v216, v216 offset:496
	ds_read_b32 v217, v217 offset:496
	s_waitcnt lgkmcnt(0)
	v_add_f32_e32 v210, v170, v210
	v_add_f32_e32 v211, v166, v211
	v_add_f32_e32 v212, v171, v212
	v_add_f32_e32 v213, v167, v213
	v_add_f32_e32 v214, v172, v214
	v_add_f32_e32 v215, v168, v215
	v_add_f32_e32 v216, v173, v216
	v_add_f32_e32 v217, v169, v217
	v_cndmask_b32_e64 v186, v19, v210, s[6:7]
	v_cndmask_b32_e64 v170, v19, v211, s[8:9]
	v_cndmask_b32_e64 v166, v19, v212, s[10:11]
	v_cndmask_b32_e64 v171, v19, v213, s[14:15]
	v_cndmask_b32_e64 v167, v19, v214, s[16:17]
	v_cndmask_b32_e64 v172, v19, v215, s[18:19]
	v_cndmask_b32_e64 v168, v19, v216, s[20:21]
	v_cndmask_b32_e64 v173, v19, v217, s[2:3]
	v_max_f32_e32 v169, v186, v166
	v_max_f32_e32 v187, v167, v168
	v_max_f32_e32 v203, v173, v173
	v_max_f32_e32 v204, v172, v172
	v_max_f32_e32 v203, v204, v203
	v_max3_f32 v203, v170, v171, v203
	v_max3_f32 v169, v169, v187, v203
	v_mov_b32_e32 v187, v169
	s_nop 1
	v_permlane16_swap_b32 v169, v187
	s_nop 1
	s_nop 0
	v_max_f32_e32 v169, v169, v187
	v_mov_b32_e32 v187, v169
	s_nop 1
	v_permlane32_swap_b32 v169, v187
	s_nop 1
	s_nop 0
	v_max3_f32 v187, v202, v169, v187
	v_cmp_gt_f32_e32 vcc, v187, v202
	s_cbranch_vccz .LBB0_598
	v_sub_f32_e32 v169, v202, v187
	v_mul_f32_e32 v169, v20, v169
	v_exp_f32_e32 v202, v169
	s_nop 0
	v_mul_f32_e32 v18, v18, v202
	v_pk_mul_f32 v[16:17], v[16:17], v[202:203] op_sel_hi:[1,0]
	v_pk_mul_f32 v[14:15], v[14:15], v[202:203] op_sel_hi:[1,0]
	v_pk_mul_f32 v[12:13], v[12:13], v[202:203] op_sel_hi:[1,0]
	v_pk_mul_f32 v[10:11], v[10:11], v[202:203] op_sel_hi:[1,0]
	v_pk_mul_f32 v[8:9], v[8:9], v[202:203] op_sel_hi:[1,0]
	v_pk_mul_f32 v[6:7], v[6:7], v[202:203] op_sel_hi:[1,0]
	v_pk_mul_f32 v[4:5], v[4:5], v[202:203] op_sel_hi:[1,0]
	v_pk_mul_f32 v[2:3], v[2:3], v[202:203] op_sel_hi:[1,0]
	s_branch .LBB0_599

; __device__ __forceinline__ float qmax(float x) { float a = x, b = x; swap16(a, b); a = fmaxf(a, b); b = a; swap32(a, b); return fmaxf(a, b); }
; __device__ __forceinline__ void softmax_pv(float& m, float& l, f32x4 (&o)[4], f32x4 s0, f32x4 s1, const bf16x8 (&vf)[4], float kL2e) {
;     float mx = fmaxf(fmaxf(fmaxf(s0[0], s0[1]), fmaxf(s0[2], s0[3])), fmaxf(fmaxf(s1[0], s1[1]), fmaxf(s1[2], s1[3])));
;     mx = qmax(mx);
;     const float mn = fmaxf(m, mx);
;     if (__builtin_amdgcn_ballot_w64(mn > m) != 0ull) {
;         const float alpha = __builtin_amdgcn_exp2f((m - mn) * kL2e);
;         l *= alpha;
; #pragma unroll
;         for (int dt = 0; dt < 4; ++dt) o[dt] = o[dt] * alpha;
;         m = mn;
.LBB0_600:
	s_cmp_ge_i32 s48, s29
	s_cbranch_scc1 .LBB0_515
	s_add_i32 s24, s49, 2
	s_min_i32 s24, s24, s31
	s_add_i32 s24, s24, s1
	s_lshl_b32 s24, s24, 6
	s_add_i32 s24, s24, s30
	s_waitcnt vmcnt(10)
	v_mad_i64_i32 v[110:111], s[56:57], s24, v242, v[182:183]
	s_ashr_i32 s25, s24, 31
	v_add_co_u32_e32 v114, vcc, 0x5000, v110
	v_lshl_add_u64 v[126:127], s[24:25], 1, v[184:185]
	s_nop 0
	v_addc_co_u32_e32 v115, vcc, 0, v111, vcc
	v_add_co_u32_e32 v122, vcc, 0x90000, v126
	global_load_dwordx4 v[102:105], v[110:111], off
	global_load_dwordx4 v[106:109], v[110:111], off offset:64
	v_addc_co_u32_e32 v123, vcc, 0, v127, vcc
	v_add_co_u32_e32 v128, vcc, 0x121000, v126
	global_load_dwordx4 v[110:113], v[114:115], off offset:2048
	s_nop 0
	global_load_dwordx4 v[114:117], v[114:115], off offset:2112
	v_addc_co_u32_e32 v129, vcc, 0, v127, vcc
	v_add_co_u32_e32 v130, vcc, 0x1b1000, v126
	global_load_dwordx4 v[118:121], v[126:127], off
	s_nop 0
	global_load_dwordx4 v[122:125], v[122:123], off offset:2048
	v_addc_co_u32_e32 v131, vcc, 0, v127, vcc
	global_load_dwordx4 v[126:129], v[128:129], off
	s_nop 0
	global_load_dwordx4 v[130:133], v[130:131], off offset:2048
	s_andn2_b64 vcc, exec, s[22:23]
	s_cbranch_vccnz .LBB0_623
	s_waitcnt vmcnt(15)
	v_mfma_f32_16x16x32_bf16 v[166:169], v[150:153], v[82:85], 0
	v_mov_b32_e32 v186, v19
	s_waitcnt vmcnt(14)
	v_mfma_f32_16x16x32_bf16 v[170:173], v[154:157], v[78:81], v[166:169]
	s_waitcnt vmcnt(13)
	v_mfma_f32_16x16x32_bf16 v[166:169], v[162:165], v[82:85], 0
	s_waitcnt vmcnt(12)
	v_mfma_f32_16x16x32_bf16 v[166:169], v[158:161], v[78:81], v[166:169]
	v_add_u32_e32 v210, s43, v198
	v_add_u32_e32 v211, s43, v197
	v_add_u32_e32 v212, s43, v196
	v_add_u32_e32 v213, s43, v195
	v_add_u32_e32 v214, s43, v194
	v_add_u32_e32 v215, s43, v193
	v_add_u32_e32 v216, s43, v192
	v_add_u32_e32 v217, s43, v191
	ds_read_b32 v210, v210 offset:992
	ds_read_b32 v211, v211 offset:992
	ds_read_b32 v212, v212 offset:992
	ds_read_b32 v213, v213 offset:992
	ds_read_b32 v214, v214 offset:992
	ds_read_b32 v215, v215 offset:992
	ds_read_b32 v216, v216 offset:992
	ds_read_b32 v217, v217 offset:992
	s_waitcnt lgkmcnt(0)
	v_add_f32_e32 v210, v170, v210
	v_add_f32_e32 v211, v166, v211
	v_add_f32_e32 v212, v171, v212
	v_add_f32_e32 v213, v167, v213
	v_add_f32_e32 v214, v172, v214
	v_add_f32_e32 v215, v168, v215
	v_add_f32_e32 v216, v173, v216
	v_add_f32_e32 v217, v169, v217
	v_cndmask_b32_e64 v186, v19, v210, s[6:7]
	v_cndmask_b32_e64 v170, v19, v211, s[8:9]
	v_cndmask_b32_e64 v166, v19, v212, s[10:11]
	v_cndmask_b32_e64 v171, v19, v213, s[14:15]
	v_cndmask_b32_e64 v167, v19, v214, s[16:17]
	v_cndmask_b32_e64 v172, v19, v215, s[18:19]
	v_cndmask_b32_e64 v168, v19, v216, s[20:21]
	v_cndmask_b32_e64 v173, v19, v217, s[2:3]
	v_max_f32_e32 v169, v186, v166
	v_max_f32_e32 v187, v167, v168
	v_max_f32_e32 v203, v173, v173
	v_max_f32_e32 v204, v172, v172
	v_max_f32_e32 v203, v204, v203
	v_max3_f32 v203, v170, v171, v203
	v_max3_f32 v169, v169, v187, v203
	v_mov_b32_e32 v187, v169
	s_nop 1
	v_permlane16_swap_b32 v169, v187
	s_nop 1
	s_nop 0
	v_max_f32_e32 v169, v169, v187
	v_mov_b32_e32 v187, v169
	s_nop 1
	v_permlane32_swap_b32 v169, v187
	s_nop 1
	s_nop 0
	v_max3_f32 v187, v199, v169, v187
	v_cmp_gt_f32_e32 vcc, v187, v199
	s_cbranch_vccz .LBB0_621
	v_sub_f32_e32 v169, v199, v187
	v_mul_f32_e32 v169, v20, v169
	v_exp_f32_e32 v204, v169
	s_nop 0
	v_mul_f32_e32 v190, v190, v204
	v_pk_mul_f32 v[100:101], v[100:101], v[204:205] op_sel_hi:[1,0]
	v_pk_mul_f32 v[98:99], v[98:99], v[204:205] op_sel_hi:[1,0]
	v_pk_mul_f32 v[96:97], v[96:97], v[204:205] op_sel_hi:[1,0]
	v_pk_mul_f32 v[94:95], v[94:95], v[204:205] op_sel_hi:[1,0]
	v_pk_mul_f32 v[92:93], v[92:93], v[204:205] op_sel_hi:[1,0]
	v_pk_mul_f32 v[90:91], v[90:91], v[204:205] op_sel_hi:[1,0]
	v_pk_mul_f32 v[88:89], v[88:89], v[204:205] op_sel_hi:[1,0]
	v_pk_mul_f32 v[86:87], v[86:87], v[204:205] op_sel_hi:[1,0]
	s_branch .LBB0_622

; __device__ __forceinline__ float qmax(float x) { float a = x, b = x; swap16(a, b); a = fmaxf(a, b); b = a; swap32(a, b); return fmaxf(a, b); }
; __device__ __forceinline__ void softmax_pv(float& m, float& l, f32x4 (&o)[4], f32x4 s0, f32x4 s1, const bf16x8 (&vf)[4], float kL2e) {
;     float mx = fmaxf(fmaxf(fmaxf(s0[0], s0[1]), fmaxf(s0[2], s0[3])), fmaxf(fmaxf(s1[0], s1[1]), fmaxf(s1[2], s1[3])));
;     mx = qmax(mx);
;     const float mn = fmaxf(m, mx);
;     if (__builtin_amdgcn_ballot_w64(mn > m) != 0ull) {
;         const float alpha = __builtin_amdgcn_exp2f((m - mn) * kL2e);
;         l *= alpha;
; #pragma unroll
;         for (int dt = 0; dt < 4; ++dt) o[dt] = o[dt] * alpha;
;         m = mn;
.LBB0_623:
	s_add_i32 s50, s50, 1
	s_cmp_ge_u32 s50, s27
	s_cselect_b64 s[22:23], -1, 0
	s_cmp_lt_u32 s50, s34
	s_cselect_b64 s[24:25], -1, 0
	s_and_b64 s[22:23], s[22:23], s[24:25]
	s_andn2_b64 vcc, exec, s[22:23]
	s_cbranch_vccnz .LBB0_644
	s_waitcnt vmcnt(15)
	v_mfma_f32_16x16x32_bf16 v[166:169], v[150:153], v[74:77], 0
	v_mov_b32_e32 v186, v19
	s_waitcnt vmcnt(14)
	v_mfma_f32_16x16x32_bf16 v[170:173], v[154:157], v[70:73], v[166:169]
	s_waitcnt vmcnt(13)
	v_mfma_f32_16x16x32_bf16 v[166:169], v[162:165], v[74:77], 0
	s_waitcnt vmcnt(12)
	v_mfma_f32_16x16x32_bf16 v[166:169], v[158:161], v[70:73], v[166:169]
	v_add_u32_e32 v210, s43, v198
	v_add_u32_e32 v211, s43, v197
	v_add_u32_e32 v212, s43, v196
	v_add_u32_e32 v213, s43, v195
	v_add_u32_e32 v214, s43, v194
	v_add_u32_e32 v215, s43, v193
	v_add_u32_e32 v216, s43, v192
	v_add_u32_e32 v217, s43, v191
	ds_read_b32 v210, v210 offset:868
	ds_read_b32 v211, v211 offset:868
	ds_read_b32 v212, v212 offset:868
	ds_read_b32 v213, v213 offset:868
	ds_read_b32 v214, v214 offset:868
	ds_read_b32 v215, v215 offset:868
	ds_read_b32 v216, v216 offset:868
	ds_read_b32 v217, v217 offset:868
	s_waitcnt lgkmcnt(0)
	v_add_f32_e32 v210, v170, v210
	v_add_f32_e32 v211, v166, v211
	v_add_f32_e32 v212, v171, v212
	v_add_f32_e32 v213, v167, v213
	v_add_f32_e32 v214, v172, v214
	v_add_f32_e32 v215, v168, v215
	v_add_f32_e32 v216, v173, v216
	v_add_f32_e32 v217, v169, v217
	v_cndmask_b32_e64 v186, v19, v210, s[6:7]
	v_cndmask_b32_e64 v170, v19, v211, s[8:9]
	v_cndmask_b32_e64 v166, v19, v212, s[10:11]
	v_cndmask_b32_e64 v171, v19, v213, s[14:15]
	v_cndmask_b32_e64 v167, v19, v214, s[16:17]
	v_cndmask_b32_e64 v172, v19, v215, s[18:19]
	v_cndmask_b32_e64 v168, v19, v216, s[20:21]
	v_cndmask_b32_e64 v173, v19, v217, s[2:3]
	v_max_f32_e32 v169, v186, v166
	v_max_f32_e32 v187, v167, v168
	v_max_f32_e32 v203, v173, v173
	v_max_f32_e32 v204, v172, v172
	v_max_f32_e32 v203, v204, v203
	v_max3_f32 v203, v170, v171, v203
	v_max3_f32 v169, v169, v187, v203
	v_mov_b32_e32 v187, v169
	s_nop 1
	v_permlane16_swap_b32 v169, v187
	s_nop 1
	s_nop 0
	v_max_f32_e32 v169, v169, v187
	v_mov_b32_e32 v187, v169
	s_nop 1
	v_permlane32_swap_b32 v169, v187
	s_nop 1
	s_nop 0
	v_max3_f32 v187, v200, v169, v187
	v_cmp_gt_f32_e32 vcc, v187, v200
	s_cbranch_vccz .LBB0_642
	v_sub_f32_e32 v169, v200, v187
	v_mul_f32_e32 v169, v20, v169
	v_exp_f32_e32 v200, v169
	s_nop 0
	v_mul_f32_e32 v189, v189, v200
	v_pk_mul_f32 v[68:69], v[68:69], v[200:201] op_sel_hi:[1,0]
	v_pk_mul_f32 v[66:67], v[66:67], v[200:201] op_sel_hi:[1,0]
	v_pk_mul_f32 v[56:57], v[56:57], v[200:201] op_sel_hi:[1,0]
	v_pk_mul_f32 v[54:55], v[54:55], v[200:201] op_sel_hi:[1,0]
	v_pk_mul_f32 v[48:49], v[48:49], v[200:201] op_sel_hi:[1,0]
	v_pk_mul_f32 v[46:47], v[46:47], v[200:201] op_sel_hi:[1,0]
	v_pk_mul_f32 v[40:41], v[40:41], v[200:201] op_sel_hi:[1,0]
	v_pk_mul_f32 v[38:39], v[38:39], v[200:201] op_sel_hi:[1,0]
	s_branch .LBB0_643

; __device__ __forceinline__ float qmax(float x) { float a = x, b = x; swap16(a, b); a = fmaxf(a, b); b = a; swap32(a, b); return fmaxf(a, b); }
; __device__ __forceinline__ void softmax_pv(float& m, float& l, f32x4 (&o)[4], f32x4 s0, f32x4 s1, const bf16x8 (&vf)[4], float kL2e) {
;     float mx = fmaxf(fmaxf(fmaxf(s0[0], s0[1]), fmaxf(s0[2], s0[3])), fmaxf(fmaxf(s1[0], s1[1]), fmaxf(s1[2], s1[3])));
;     mx = qmax(mx);
;     const float mn = fmaxf(m, mx);
;     if (__builtin_amdgcn_ballot_w64(mn > m) != 0ull) {
;         const float alpha = __builtin_amdgcn_exp2f((m - mn) * kL2e);
;         l *= alpha;
; #pragma unroll
;         for (int dt = 0; dt < 4; ++dt) o[dt] = o[dt] * alpha;
;         m = mn;
.LBB0_644:
	s_cmp_ge_u32 s50, s28
	s_cselect_b64 s[22:23], -1, 0
	s_cmp_lt_u32 s50, s35
	s_cselect_b64 s[24:25], -1, 0
	s_and_b64 s[22:23], s[22:23], s[24:25]
	s_andn2_b64 vcc, exec, s[22:23]
	s_cbranch_vccnz .LBB0_665
	s_waitcnt vmcnt(15)
	v_mfma_f32_16x16x32_bf16 v[166:169], v[150:153], v[62:65], 0
	v_mov_b32_e32 v186, v19
	s_waitcnt vmcnt(14)
	v_mfma_f32_16x16x32_bf16 v[170:173], v[154:157], v[58:61], v[166:169]
	s_waitcnt vmcnt(13)
	v_mfma_f32_16x16x32_bf16 v[166:169], v[162:165], v[62:65], 0
	s_waitcnt vmcnt(12)
	v_mfma_f32_16x16x32_bf16 v[166:169], v[158:161], v[58:61], v[166:169]
	v_add_u32_e32 v210, s43, v198
	v_add_u32_e32 v211, s43, v197
	v_add_u32_e32 v212, s43, v196
	v_add_u32_e32 v213, s43, v195
	v_add_u32_e32 v214, s43, v194
	v_add_u32_e32 v215, s43, v193
	v_add_u32_e32 v216, s43, v192
	v_add_u32_e32 v217, s43, v191
	ds_read_b32 v210, v210 offset:744
	ds_read_b32 v211, v211 offset:744
	ds_read_b32 v212, v212 offset:744
	ds_read_b32 v213, v213 offset:744
	ds_read_b32 v214, v214 offset:744
	ds_read_b32 v215, v215 offset:744
	ds_read_b32 v216, v216 offset:744
	ds_read_b32 v217, v217 offset:744
	s_waitcnt lgkmcnt(0)
	v_add_f32_e32 v210, v170, v210
	v_add_f32_e32 v211, v166, v211
	v_add_f32_e32 v212, v171, v212
	v_add_f32_e32 v213, v167, v213
	v_add_f32_e32 v214, v172, v214
	v_add_f32_e32 v215, v168, v215
	v_add_f32_e32 v216, v173, v216
	v_add_f32_e32 v217, v169, v217
	v_cndmask_b32_e64 v186, v19, v210, s[6:7]
	v_cndmask_b32_e64 v170, v19, v211, s[8:9]
	v_cndmask_b32_e64 v166, v19, v212, s[10:11]
	v_cndmask_b32_e64 v171, v19, v213, s[14:15]
	v_cndmask_b32_e64 v167, v19, v214, s[16:17]
	v_cndmask_b32_e64 v172, v19, v215, s[18:19]
	v_cndmask_b32_e64 v168, v19, v216, s[20:21]
	v_cndmask_b32_e64 v173, v19, v217, s[2:3]
	v_max_f32_e32 v169, v186, v166
	v_max_f32_e32 v187, v167, v168
	v_max_f32_e32 v203, v173, v173
	v_max_f32_e32 v204, v172, v172
	v_max_f32_e32 v203, v204, v203
	v_max3_f32 v203, v170, v171, v203
	v_max3_f32 v169, v169, v187, v203
	v_mov_b32_e32 v187, v169
	s_nop 1
	v_permlane16_swap_b32 v169, v187
	s_nop 1
	s_nop 0
	v_max_f32_e32 v169, v169, v187
	v_mov_b32_e32 v187, v169
	s_nop 1
	v_permlane32_swap_b32 v169, v187
	s_nop 1
	s_nop 0
	v_max3_f32 v187, v201, v169, v187
	v_cmp_gt_f32_e32 vcc, v187, v201
	s_cbranch_vccz .LBB0_663
	v_sub_f32_e32 v169, v201, v187
	v_mul_f32_e32 v169, v20, v169
	v_exp_f32_e32 v204, v169
	s_nop 0
	v_mul_f32_e32 v0, v0, v204
	v_pk_mul_f32 v[36:37], v[36:37], v[204:205] op_sel_hi:[1,0]
	v_pk_mul_f32 v[34:35], v[34:35], v[204:205] op_sel_hi:[1,0]
	v_pk_mul_f32 v[32:33], v[32:33], v[204:205] op_sel_hi:[1,0]
	v_pk_mul_f32 v[30:31], v[30:31], v[204:205] op_sel_hi:[1,0]
	v_pk_mul_f32 v[28:29], v[28:29], v[204:205] op_sel_hi:[1,0]
	v_pk_mul_f32 v[26:27], v[26:27], v[204:205] op_sel_hi:[1,0]
	v_pk_mul_f32 v[24:25], v[24:25], v[204:205] op_sel_hi:[1,0]
	v_pk_mul_f32 v[22:23], v[22:23], v[204:205] op_sel_hi:[1,0]
	s_branch .LBB0_664

.LBB0_665:
	s_cmp_lt_u32 s50, s26
	s_cbranch_scc1 .LBB0_515
	s_waitcnt vmcnt(15)
	v_mfma_f32_16x16x32_bf16 v[150:153], v[150:153], v[50:53], 0
	s_waitcnt vmcnt(14)
	v_mfma_f32_16x16x32_bf16 v[154:157], v[154:157], v[42:45], v[150:153]
	s_waitcnt vmcnt(13)
	v_mfma_f32_16x16x32_bf16 v[150:153], v[162:165], v[50:53], 0
	v_mov_b32_e32 v162, v19
	s_waitcnt vmcnt(12)
	v_mfma_f32_16x16x32_bf16 v[150:153], v[158:161], v[42:45], v[150:153]
	v_add_u32_e32 v210, s43, v198
	v_add_u32_e32 v211, s43, v197
	v_add_u32_e32 v212, s43, v196
	v_add_u32_e32 v213, s43, v195
	v_add_u32_e32 v214, s43, v194
	v_add_u32_e32 v215, s43, v193
	v_add_u32_e32 v216, s43, v192
	v_add_u32_e32 v217, s43, v191
	ds_read_b32 v210, v210 offset:620
	ds_read_b32 v211, v211 offset:620
	ds_read_b32 v212, v212 offset:620
	ds_read_b32 v213, v213 offset:620
	ds_read_b32 v214, v214 offset:620
	ds_read_b32 v215, v215 offset:620
	ds_read_b32 v216, v216 offset:620
	ds_read_b32 v217, v217 offset:620
	s_waitcnt lgkmcnt(0)
	v_add_f32_e32 v210, v154, v210
	v_add_f32_e32 v211, v150, v211
	v_add_f32_e32 v212, v155, v212
	v_add_f32_e32 v213, v151, v213
	v_add_f32_e32 v214, v156, v214
	v_add_f32_e32 v215, v152, v215
	v_add_f32_e32 v216, v157, v216
	v_add_f32_e32 v217, v153, v217
	v_cndmask_b32_e64 v162, v19, v210, s[6:7]
	v_cndmask_b32_e64 v154, v19, v211, s[8:9]
	v_cndmask_b32_e64 v150, v19, v212, s[10:11]
	v_cndmask_b32_e64 v155, v19, v213, s[14:15]
	v_cndmask_b32_e64 v151, v19, v214, s[16:17]
	v_cndmask_b32_e64 v156, v19, v215, s[18:19]
	v_cndmask_b32_e64 v152, v19, v216, s[20:21]
	v_cndmask_b32_e64 v157, v19, v217, s[2:3]
	s_branch .LBB0_512
